# online softmax keeps the old running reference (no accumulator rescale) unless a row max of the wave grew by more than 8 log2 units; exact by shift invariance; all 10 attention sites
# speedup vs baseline: 1.0335x; 1.0067x over previous
.Lj3ld_norka:
	s_or_b64 exec, exec, s[6:7]
	s_waitcnt lgkmcnt(0)
	v_mfma_f32_32x32x16_bf16 v[146:161], v[240:243], v[246:249], v[146:161]
	s_nop 11
	v_pk_add_f32 v[146:147], v[130:131], v[146:147]
	v_pk_add_f32 v[132:133], v[132:133], v[148:149]
	v_max_f32_e32 v130, v146, v147
	v_pk_add_f32 v[134:135], v[134:135], v[150:151]
	v_max3_f32 v130, v130, v132, v133
	v_pk_add_f32 v[136:137], v[136:137], v[152:153]
	v_max3_f32 v130, v130, v134, v135
	v_mbcnt_hi_u32_b32 v131, -1, v217
	v_pk_add_f32 v[138:139], v[138:139], v[154:155]
	v_max3_f32 v130, v130, v136, v137
	v_and_b32_e32 v149, 64, v131
	v_pk_add_f32 v[140:141], v[140:141], v[156:157]
	v_max3_f32 v130, v130, v138, v139
	v_xor_b32_e32 v148, 32, v131
	v_add_u32_e32 v149, 64, v149
	v_pk_add_f32 v[142:143], v[142:143], v[158:159]
	v_max3_f32 v130, v130, v140, v141
	v_cmp_lt_i32_e32 vcc, v148, v149
	v_pk_add_f32 v[144:145], v[144:145], v[160:161]
	v_max3_f32 v130, v130, v142, v143
	v_cndmask_b32_e32 v131, v131, v148, vcc
	v_max3_f32 v130, v130, v144, v145
	v_lshlrev_b32_e32 v131, 2, v131
	ds_bpermute_b32 v131, v131, v130
	s_waitcnt lgkmcnt(0)
	ds_read_b64_tr_b16 v[232:233], v222
	ds_read_b64_tr_b16 v[234:235], v222 offset:4736
	ds_read_b64_tr_b16 v[236:237], v222 offset:64
	ds_read_b64_tr_b16 v[238:239], v222 offset:4800
	ds_read_b64_tr_b16 v[240:241], v222 offset:128
	ds_read_b64_tr_b16 v[242:243], v222 offset:4864
	ds_read_b64_tr_b16 v[246:247], v222 offset:192
	ds_read_b64_tr_b16 v[248:249], v222 offset:4928
	v_max3_f32 v229, v230, v130, v131
	v_sub_f32_e32 v130, v230, v229
	v_cmp_gt_f32_e32 vcc, 0xc1000000, v130
	s_cbranch_vccnz .Llazy0_full
	v_mov_b32_e32 v229, v230
	v_mov_b32_e32 v130, 1.0
	s_branch .LBB0_946
.Llazy0_full:
	v_exp_f32_e32 v130, v130
	s_nop 0
	v_cmp_neq_f32_e32 vcc, 1.0, v130
	s_cbranch_vccz .LBB0_946
	v_pk_mul_f32 v[128:129], v[128:129], v[130:131] op_sel_hi:[1,0]
	v_pk_mul_f32 v[126:127], v[126:127], v[130:131] op_sel_hi:[1,0]
	v_pk_mul_f32 v[124:125], v[124:125], v[130:131] op_sel_hi:[1,0]
	v_pk_mul_f32 v[122:123], v[122:123], v[130:131] op_sel_hi:[1,0]
	v_pk_mul_f32 v[120:121], v[120:121], v[130:131] op_sel_hi:[1,0]
	v_pk_mul_f32 v[118:119], v[118:119], v[130:131] op_sel_hi:[1,0]
	v_pk_mul_f32 v[116:117], v[116:117], v[130:131] op_sel_hi:[1,0]
	v_pk_mul_f32 v[114:115], v[114:115], v[130:131] op_sel_hi:[1,0]
	v_pk_mul_f32 v[112:113], v[112:113], v[130:131] op_sel_hi:[1,0]
	v_pk_mul_f32 v[110:111], v[110:111], v[130:131] op_sel_hi:[1,0]
	v_pk_mul_f32 v[108:109], v[108:109], v[130:131] op_sel_hi:[1,0]
	v_pk_mul_f32 v[106:107], v[106:107], v[130:131] op_sel_hi:[1,0]
	v_pk_mul_f32 v[104:105], v[104:105], v[130:131] op_sel_hi:[1,0]
	v_pk_mul_f32 v[102:103], v[102:103], v[130:131] op_sel_hi:[1,0]
	v_pk_mul_f32 v[100:101], v[100:101], v[130:131] op_sel_hi:[1,0]
	v_pk_mul_f32 v[98:99], v[98:99], v[130:131] op_sel_hi:[1,0]
	v_pk_mul_f32 v[96:97], v[96:97], v[130:131] op_sel_hi:[1,0]
	v_pk_mul_f32 v[94:95], v[94:95], v[130:131] op_sel_hi:[1,0]
	v_pk_mul_f32 v[92:93], v[92:93], v[130:131] op_sel_hi:[1,0]
	v_pk_mul_f32 v[90:91], v[90:91], v[130:131] op_sel_hi:[1,0]
	v_pk_mul_f32 v[88:89], v[88:89], v[130:131] op_sel_hi:[1,0]
	v_pk_mul_f32 v[86:87], v[86:87], v[130:131] op_sel_hi:[1,0]
	v_pk_mul_f32 v[84:85], v[84:85], v[130:131] op_sel_hi:[1,0]
	v_pk_mul_f32 v[82:83], v[82:83], v[130:131] op_sel_hi:[1,0]
	v_pk_mul_f32 v[80:81], v[80:81], v[130:131] op_sel_hi:[1,0]
	v_pk_mul_f32 v[78:79], v[78:79], v[130:131] op_sel_hi:[1,0]
	v_pk_mul_f32 v[76:77], v[76:77], v[130:131] op_sel_hi:[1,0]
	v_pk_mul_f32 v[74:75], v[74:75], v[130:131] op_sel_hi:[1,0]
	v_pk_mul_f32 v[72:73], v[72:73], v[130:131] op_sel_hi:[1,0]
	v_pk_mul_f32 v[70:71], v[70:71], v[130:131] op_sel_hi:[1,0]
	v_pk_mul_f32 v[68:69], v[68:69], v[130:131] op_sel_hi:[1,0]
	v_pk_mul_f32 v[66:67], v[66:67], v[130:131] op_sel_hi:[1,0]
	v_pk_mul_f32 v[64:65], v[64:65], v[130:131] op_sel_hi:[1,0]
	v_pk_mul_f32 v[62:63], v[62:63], v[130:131] op_sel_hi:[1,0]
	v_pk_mul_f32 v[60:61], v[60:61], v[130:131] op_sel_hi:[1,0]
	v_pk_mul_f32 v[58:59], v[58:59], v[130:131] op_sel_hi:[1,0]
	v_pk_mul_f32 v[56:57], v[56:57], v[130:131] op_sel_hi:[1,0]
	v_pk_mul_f32 v[54:55], v[54:55], v[130:131] op_sel_hi:[1,0]
	v_pk_mul_f32 v[52:53], v[52:53], v[130:131] op_sel_hi:[1,0]
	v_pk_mul_f32 v[50:51], v[50:51], v[130:131] op_sel_hi:[1,0]
	v_pk_mul_f32 v[48:49], v[48:49], v[130:131] op_sel_hi:[1,0]
	v_pk_mul_f32 v[46:47], v[46:47], v[130:131] op_sel_hi:[1,0]
	v_pk_mul_f32 v[44:45], v[44:45], v[130:131] op_sel_hi:[1,0]
	v_pk_mul_f32 v[42:43], v[42:43], v[130:131] op_sel_hi:[1,0]
	v_pk_mul_f32 v[40:41], v[40:41], v[130:131] op_sel_hi:[1,0]
	v_pk_mul_f32 v[38:39], v[38:39], v[130:131] op_sel_hi:[1,0]
	v_pk_mul_f32 v[36:37], v[36:37], v[130:131] op_sel_hi:[1,0]
	v_pk_mul_f32 v[34:35], v[34:35], v[130:131] op_sel_hi:[1,0]
	v_pk_mul_f32 v[32:33], v[32:33], v[130:131] op_sel_hi:[1,0]
	v_pk_mul_f32 v[30:31], v[30:31], v[130:131] op_sel_hi:[1,0]
	v_pk_mul_f32 v[28:29], v[28:29], v[130:131] op_sel_hi:[1,0]
	v_pk_mul_f32 v[26:27], v[26:27], v[130:131] op_sel_hi:[1,0]
	v_pk_mul_f32 v[24:25], v[24:25], v[130:131] op_sel_hi:[1,0]
	v_pk_mul_f32 v[22:23], v[22:23], v[130:131] op_sel_hi:[1,0]
	v_pk_mul_f32 v[20:21], v[20:21], v[130:131] op_sel_hi:[1,0]
	v_pk_mul_f32 v[18:19], v[18:19], v[130:131] op_sel_hi:[1,0]
	v_pk_mul_f32 v[16:17], v[16:17], v[130:131] op_sel_hi:[1,0]
	v_pk_mul_f32 v[14:15], v[14:15], v[130:131] op_sel_hi:[1,0]
	v_pk_mul_f32 v[12:13], v[12:13], v[130:131] op_sel_hi:[1,0]
	v_pk_mul_f32 v[10:11], v[10:11], v[130:131] op_sel_hi:[1,0]
	v_pk_mul_f32 v[8:9], v[8:9], v[130:131] op_sel_hi:[1,0]
	v_pk_mul_f32 v[6:7], v[6:7], v[130:131] op_sel_hi:[1,0]
	v_pk_mul_f32 v[4:5], v[4:5], v[130:131] op_sel_hi:[1,0]
	v_pk_mul_f32 v[2:3], v[2:3], v[130:131] op_sel_hi:[1,0]

.LBB0_954:
	s_or_b64 exec, exec, s[10:11]
	s_cmp_gt_i32 s40, 5
	v_add_u32_e32 v182, v224, v198
	s_cbranch_scc1 .LBB0_958
	ds_read_b128 v[130:133], v182
	ds_read_b128 v[134:137], v223
	ds_read_b128 v[146:149], v182 offset:32
	ds_read_b128 v[150:153], v223 offset:1024
	ds_read_b128 v[184:187], v182 offset:64
	ds_read_b128 v[188:191], v223 offset:2048
	s_waitcnt lgkmcnt(4)
	v_mfma_f32_32x32x16_bf16 v[130:145], v[130:133], v[134:137], 0
	s_waitcnt lgkmcnt(2)
	v_mfma_f32_32x32x16_bf16 v[146:161], v[146:149], v[150:153], 0
	s_waitcnt lgkmcnt(0)
	v_mfma_f32_32x32x16_bf16 v[130:145], v[184:187], v[188:191], v[130:145]
	ds_read_b128 v[184:187], v182 offset:96
	ds_read_b128 v[188:191], v223 offset:3072
	s_waitcnt lgkmcnt(0)
	v_mfma_f32_32x32x16_bf16 v[146:161], v[184:187], v[188:191], v[146:161]
	ds_read_b128 v[184:187], v182 offset:128
	ds_read_b128 v[188:191], v223 offset:4096
	s_waitcnt lgkmcnt(0)
	v_mfma_f32_32x32x16_bf16 v[130:145], v[184:187], v[188:191], v[130:145]
	ds_read_b128 v[184:187], v182 offset:160
	ds_read_b128 v[188:191], v223 offset:5120
	s_waitcnt lgkmcnt(0)
	v_mfma_f32_32x32x16_bf16 v[146:161], v[184:187], v[188:191], v[146:161]
	ds_read_b128 v[184:187], v182 offset:192
	ds_read_b128 v[188:191], v223 offset:6144
	s_waitcnt lgkmcnt(0)
	v_mfma_f32_32x32x16_bf16 v[130:145], v[184:187], v[188:191], v[130:145]
	ds_read_b128 v[184:187], v182 offset:224
	ds_read_b128 v[188:191], v223 offset:7168
	s_waitcnt lgkmcnt(0)
	v_mfma_f32_32x32x16_bf16 v[146:161], v[184:187], v[188:191], v[146:161]
	ds_read_b128 v[184:187], v182 offset:256
	ds_read_b128 v[188:191], v223 offset:8192
	s_waitcnt lgkmcnt(0)
	v_mfma_f32_32x32x16_bf16 v[130:145], v[184:187], v[188:191], v[130:145]
	ds_read_b128 v[184:187], v182 offset:288
	ds_read_b128 v[188:191], v223 offset:9216
	s_waitcnt lgkmcnt(0)
	v_mfma_f32_32x32x16_bf16 v[146:161], v[184:187], v[188:191], v[146:161]
	ds_read_b128 v[184:187], v182 offset:320
	ds_read_b128 v[188:191], v223 offset:10240
	s_waitcnt lgkmcnt(0)
	v_mfma_f32_32x32x16_bf16 v[130:145], v[184:187], v[188:191], v[130:145]
	ds_read_b128 v[184:187], v182 offset:352
	ds_read_b128 v[188:191], v223 offset:11264
	s_waitcnt lgkmcnt(0)
	v_mfma_f32_32x32x16_bf16 v[146:161], v[184:187], v[188:191], v[146:161]
	ds_read_b128 v[184:187], v182 offset:384
	ds_read_b128 v[188:191], v223 offset:12288
	s_waitcnt lgkmcnt(0)
	v_mfma_f32_32x32x16_bf16 v[130:145], v[184:187], v[188:191], v[130:145]
	ds_read_b128 v[184:187], v182 offset:416
	ds_read_b128 v[188:191], v223 offset:13312
	s_waitcnt lgkmcnt(0)
	v_mfma_f32_32x32x16_bf16 v[146:161], v[184:187], v[188:191], v[146:161]
	ds_read_b128 v[184:187], v182 offset:448
	ds_read_b128 v[188:191], v223 offset:14336
	s_waitcnt lgkmcnt(0)
	v_mfma_f32_32x32x16_bf16 v[130:145], v[184:187], v[188:191], v[130:145]
	ds_read_b128 v[184:187], v182 offset:480
	ds_read_b128 v[188:191], v223 offset:15360
	s_waitcnt lgkmcnt(0)
	v_mfma_f32_32x32x16_bf16 v[146:161], v[184:187], v[188:191], v[146:161]
	ds_read_b128 v[184:187], v182 offset:512
	ds_read_b128 v[188:191], v223 offset:16384
	s_waitcnt lgkmcnt(0)
	v_mfma_f32_32x32x16_bf16 v[130:145], v[184:187], v[188:191], v[130:145]
	ds_read_b128 v[184:187], v182 offset:544
	ds_read_b128 v[188:191], v223 offset:17408
	s_waitcnt lgkmcnt(0)
	v_mfma_f32_32x32x16_bf16 v[146:161], v[184:187], v[188:191], v[146:161]
	s_nop 11
	v_pk_add_f32 v[146:147], v[130:131], v[146:147]
	v_pk_add_f32 v[132:133], v[132:133], v[148:149]
	v_max_f32_e32 v130, v146, v147
	v_pk_add_f32 v[134:135], v[134:135], v[150:151]
	v_max3_f32 v130, v130, v132, v133
	v_pk_add_f32 v[136:137], v[136:137], v[152:153]
	v_max3_f32 v130, v130, v134, v135
	v_mbcnt_hi_u32_b32 v131, -1, v217
	v_pk_add_f32 v[138:139], v[138:139], v[154:155]
	v_max3_f32 v130, v130, v136, v137
	v_and_b32_e32 v149, 64, v131
	v_pk_add_f32 v[140:141], v[140:141], v[156:157]
	v_max3_f32 v130, v130, v138, v139
	v_xor_b32_e32 v148, 32, v131
	v_add_u32_e32 v149, 64, v149
	v_pk_add_f32 v[142:143], v[142:143], v[158:159]
	v_max3_f32 v130, v130, v140, v141
	v_cmp_lt_i32_e32 vcc, v148, v149
	v_pk_add_f32 v[144:145], v[144:145], v[160:161]
	v_max3_f32 v130, v130, v142, v143
	v_cndmask_b32_e32 v131, v131, v148, vcc
	v_max3_f32 v130, v130, v144, v145
	v_lshlrev_b32_e32 v131, 2, v131
	ds_bpermute_b32 v131, v131, v130
	s_waitcnt lgkmcnt(0)
	v_max3_f32 v184, v229, v130, v131
	v_sub_f32_e32 v130, v229, v184
	v_cmp_gt_f32_e32 vcc, 0xc1000000, v130
	s_cbranch_vccnz .Llazy1_full
	v_mov_b32_e32 v184, v229
	v_mov_b32_e32 v130, 1.0
	s_branch .LBB0_957

.LBB0_963:
	s_andn2_b64 vcc, exec, s[6:7]
	s_cbranch_vccnz .LBB0_967
	ds_read_b128 v[130:133], v182
	ds_read_b128 v[134:137], v223
	ds_read_b128 v[146:149], v182 offset:32
	ds_read_b128 v[150:153], v223 offset:1024
	ds_read_b128 v[162:165], v182 offset:64
	ds_read_b128 v[166:169], v223 offset:2048
	s_waitcnt lgkmcnt(4)
	v_mfma_f32_32x32x16_bf16 v[130:145], v[130:133], v[134:137], 0
	s_waitcnt lgkmcnt(2)
	v_mfma_f32_32x32x16_bf16 v[146:161], v[146:149], v[150:153], 0
	s_waitcnt lgkmcnt(0)
	v_mfma_f32_32x32x16_bf16 v[130:145], v[162:165], v[166:169], v[130:145]
	ds_read_b128 v[162:165], v182 offset:96
	ds_read_b128 v[166:169], v223 offset:3072
	s_waitcnt lgkmcnt(0)
	v_mfma_f32_32x32x16_bf16 v[146:161], v[162:165], v[166:169], v[146:161]
	ds_read_b128 v[162:165], v182 offset:128
	ds_read_b128 v[166:169], v223 offset:4096
	s_waitcnt lgkmcnt(0)
	v_mfma_f32_32x32x16_bf16 v[130:145], v[162:165], v[166:169], v[130:145]
	ds_read_b128 v[162:165], v182 offset:160
	ds_read_b128 v[166:169], v223 offset:5120
	s_waitcnt lgkmcnt(0)
	v_mfma_f32_32x32x16_bf16 v[146:161], v[162:165], v[166:169], v[146:161]
	ds_read_b128 v[162:165], v182 offset:192
	ds_read_b128 v[166:169], v223 offset:6144
	s_waitcnt lgkmcnt(0)
	v_mfma_f32_32x32x16_bf16 v[130:145], v[162:165], v[166:169], v[130:145]
	ds_read_b128 v[162:165], v182 offset:224
	ds_read_b128 v[166:169], v223 offset:7168
	s_waitcnt lgkmcnt(0)
	v_mfma_f32_32x32x16_bf16 v[146:161], v[162:165], v[166:169], v[146:161]
	ds_read_b128 v[162:165], v182 offset:256
	ds_read_b128 v[166:169], v223 offset:8192
	s_waitcnt lgkmcnt(0)
	v_mfma_f32_32x32x16_bf16 v[130:145], v[162:165], v[166:169], v[130:145]
	ds_read_b128 v[162:165], v182 offset:288
	ds_read_b128 v[166:169], v223 offset:9216
	s_waitcnt lgkmcnt(0)
	v_mfma_f32_32x32x16_bf16 v[146:161], v[162:165], v[166:169], v[146:161]
	ds_read_b128 v[162:165], v182 offset:320
	ds_read_b128 v[166:169], v223 offset:10240
	s_waitcnt lgkmcnt(0)
	v_mfma_f32_32x32x16_bf16 v[130:145], v[162:165], v[166:169], v[130:145]
	ds_read_b128 v[162:165], v182 offset:352
	ds_read_b128 v[166:169], v223 offset:11264
	s_waitcnt lgkmcnt(0)
	v_mfma_f32_32x32x16_bf16 v[146:161], v[162:165], v[166:169], v[146:161]
	ds_read_b128 v[162:165], v182 offset:384
	ds_read_b128 v[166:169], v223 offset:12288
	s_waitcnt lgkmcnt(0)
	v_mfma_f32_32x32x16_bf16 v[130:145], v[162:165], v[166:169], v[130:145]
	ds_read_b128 v[162:165], v182 offset:416
	ds_read_b128 v[166:169], v223 offset:13312
	s_waitcnt lgkmcnt(0)
	v_mfma_f32_32x32x16_bf16 v[146:161], v[162:165], v[166:169], v[146:161]
	ds_read_b128 v[162:165], v182 offset:448
	ds_read_b128 v[166:169], v223 offset:14336
	s_waitcnt lgkmcnt(0)
	v_mfma_f32_32x32x16_bf16 v[130:145], v[162:165], v[166:169], v[130:145]
	ds_read_b128 v[162:165], v182 offset:480
	ds_read_b128 v[166:169], v223 offset:15360
	s_waitcnt lgkmcnt(0)
	v_mfma_f32_32x32x16_bf16 v[146:161], v[162:165], v[166:169], v[146:161]
	ds_read_b128 v[162:165], v182 offset:512
	ds_read_b128 v[166:169], v223 offset:16384
	s_waitcnt lgkmcnt(0)
	v_mfma_f32_32x32x16_bf16 v[130:145], v[162:165], v[166:169], v[130:145]
	ds_read_b128 v[162:165], v182 offset:544
	ds_read_b128 v[166:169], v223 offset:17408
	s_waitcnt lgkmcnt(0)
	v_mfma_f32_32x32x16_bf16 v[146:161], v[162:165], v[166:169], v[146:161]
	s_nop 11
	v_pk_add_f32 v[146:147], v[130:131], v[146:147]
	v_pk_add_f32 v[132:133], v[132:133], v[148:149]
	v_max_f32_e32 v130, v146, v147
	v_pk_add_f32 v[134:135], v[134:135], v[150:151]
	v_max3_f32 v130, v130, v132, v133
	v_pk_add_f32 v[136:137], v[136:137], v[152:153]
	v_max3_f32 v130, v130, v134, v135
	v_pk_add_f32 v[138:139], v[138:139], v[154:155]
	v_max3_f32 v130, v130, v136, v137
	v_and_b32_e32 v131, 64, v218
	v_pk_add_f32 v[140:141], v[140:141], v[156:157]
	v_max3_f32 v130, v130, v138, v139
	v_xor_b32_e32 v149, 32, v218
	v_add_u32_e32 v150, 64, v131
	v_pk_add_f32 v[142:143], v[142:143], v[158:159]
	v_max3_f32 v130, v130, v140, v141
	v_cmp_lt_i32_e32 vcc, v149, v150
	v_pk_add_f32 v[144:145], v[144:145], v[160:161]
	v_max3_f32 v130, v130, v142, v143
	v_cndmask_b32_e32 v131, v218, v149, vcc
	v_max3_f32 v130, v130, v144, v145
	v_lshlrev_b32_e32 v131, 2, v131
	ds_bpermute_b32 v131, v131, v130
	s_waitcnt lgkmcnt(0)
	v_max3_f32 v148, v184, v130, v131
	v_sub_f32_e32 v130, v184, v148
	v_cmp_gt_f32_e32 vcc, 0xc1000000, v130
	s_cbranch_vccnz .Llazy2_full
	v_mov_b32_e32 v148, v184
	v_mov_b32_e32 v130, 1.0
	s_branch .LBB0_966

.LBB0_1005:
	s_nop 0
	v_max3_f32 v64, v171, v169, v52
	v_max3_f32 v64, v64, v166, v53
	v_max3_f32 v64, v64, v167, v168
	v_max3_f32 v64, v64, v170, v54
	v_max3_f32 v64, v64, v164, v55
	v_max3_f32 v64, v64, v165, v56
	v_max3_f32 v64, v64, v162, v57
	v_max3_f32 v64, v64, v163, v58
	v_max3_f32 v64, v64, v160, v59
	v_max3_f32 v64, v64, v161, v60
	v_max3_f32 v64, v64, v158, v61
	v_max3_f32 v64, v64, v159, v62
	v_max3_f32 v64, v64, v156, v63
	v_max3_f32 v64, v64, v157, v50
	v_max3_f32 v64, v64, v154, v51
	v_max_f32_e32 v64, v64, v155
	v_and_b32_e32 v182, 64, v218
	v_xor_b32_e32 v65, 32, v218
	v_add_u32_e32 v182, 64, v182
	v_cmp_lt_i32_e32 vcc, v65, v182
	s_nop 1
	v_cndmask_b32_e32 v65, v218, v65, vcc
	v_lshlrev_b32_e32 v65, 2, v65
	ds_bpermute_b32 v65, v65, v64
	s_waitcnt lgkmcnt(0)
	v_max3_f32 v182, v181, v64, v65
	v_sub_f32_e32 v64, v181, v182
	v_cmp_gt_f32_e32 vcc, 0xc1000000, v64
	s_cbranch_vccnz .Llazy3_full
	v_mov_b32_e32 v182, v181
	v_mov_b32_e32 v64, 1.0
	s_branch .LBB0_1007
.Llazy3_full:
	v_exp_f32_e32 v64, v64
	s_nop 0
	v_cmp_neq_f32_e32 vcc, 1.0, v64
	s_cbranch_vccz .LBB0_1007
	v_pk_mul_f32 v[18:19], v[18:19], v[64:65] op_sel_hi:[1,0]
	v_pk_mul_f32 v[16:17], v[16:17], v[64:65] op_sel_hi:[1,0]
	v_pk_mul_f32 v[14:15], v[14:15], v[64:65] op_sel_hi:[1,0]
	v_pk_mul_f32 v[12:13], v[12:13], v[64:65] op_sel_hi:[1,0]
	v_pk_mul_f32 v[10:11], v[10:11], v[64:65] op_sel_hi:[1,0]
	v_pk_mul_f32 v[8:9], v[8:9], v[64:65] op_sel_hi:[1,0]
	v_pk_mul_f32 v[6:7], v[6:7], v[64:65] op_sel_hi:[1,0]
	v_pk_mul_f32 v[4:5], v[4:5], v[64:65] op_sel_hi:[1,0]
	v_pk_mul_f32 v[40:41], v[40:41], v[64:65] op_sel_hi:[1,0]
	v_pk_mul_f32 v[38:39], v[38:39], v[64:65] op_sel_hi:[1,0]
	v_pk_mul_f32 v[36:37], v[36:37], v[64:65] op_sel_hi:[1,0]
	v_pk_mul_f32 v[34:35], v[34:35], v[64:65] op_sel_hi:[1,0]
	v_pk_mul_f32 v[32:33], v[32:33], v[64:65] op_sel_hi:[1,0]
	v_pk_mul_f32 v[30:31], v[30:31], v[64:65] op_sel_hi:[1,0]
	v_pk_mul_f32 v[28:29], v[28:29], v[64:65] op_sel_hi:[1,0]
	v_pk_mul_f32 v[26:27], v[26:27], v[64:65] op_sel_hi:[1,0]

.LBB0_1051:
	s_waitcnt lgkmcnt(0)
	s_nop 3
	s_nop 0
	v_max3_f32 v178, v99, v115, v100
	v_max3_f32 v178, v178, v116, v101
	v_max3_f32 v178, v178, v117, v114
	v_max3_f32 v178, v178, v98, v102
	v_max3_f32 v178, v178, v118, v103
	v_max3_f32 v178, v178, v119, v104
	v_max3_f32 v178, v178, v120, v105
	v_max3_f32 v178, v178, v121, v106
	v_max3_f32 v178, v178, v122, v107
	v_max3_f32 v178, v178, v123, v108
	v_max3_f32 v178, v178, v124, v109
	v_max3_f32 v178, v178, v125, v110
	v_max3_f32 v178, v178, v126, v111
	v_max3_f32 v178, v178, v127, v112
	v_max3_f32 v178, v178, v128, v113
	v_max_f32_e32 v178, v178, v129
	v_and_b32_e32 v180, 64, v218
	v_xor_b32_e32 v179, 32, v218
	v_add_u32_e32 v180, 64, v180
	v_cmp_lt_i32_e32 vcc, v179, v180
	s_nop 1
	v_cndmask_b32_e32 v179, v218, v179, vcc
	v_lshlrev_b32_e32 v179, 2, v179
	ds_bpermute_b32 v179, v179, v178
	s_waitcnt lgkmcnt(0)
	v_max3_f32 v207, v205, v178, v179
	v_sub_f32_e32 v178, v205, v207
	v_cmp_gt_f32_e32 vcc, 0xc1000000, v178
	s_cbranch_vccnz .Llazy4_full
	v_mov_b32_e32 v207, v205
	v_mov_b32_e32 v178, 1.0
	s_branch .LBB0_1053
.Llazy4_full:
	v_exp_f32_e32 v178, v178
	s_nop 0
	v_cmp_neq_f32_e32 vcc, 1.0, v178
	s_cbranch_vccz .LBB0_1053
	v_pk_mul_f32 v[64:65], v[64:65], v[178:179] op_sel_hi:[1,0]
	v_pk_mul_f32 v[62:63], v[62:63], v[178:179] op_sel_hi:[1,0]
	v_pk_mul_f32 v[60:61], v[60:61], v[178:179] op_sel_hi:[1,0]
	v_pk_mul_f32 v[58:59], v[58:59], v[178:179] op_sel_hi:[1,0]
	v_pk_mul_f32 v[56:57], v[56:57], v[178:179] op_sel_hi:[1,0]
	v_pk_mul_f32 v[54:55], v[54:55], v[178:179] op_sel_hi:[1,0]
	v_pk_mul_f32 v[52:53], v[52:53], v[178:179] op_sel_hi:[1,0]
	v_pk_mul_f32 v[50:51], v[50:51], v[178:179] op_sel_hi:[1,0]
	v_pk_mul_f32 v[48:49], v[48:49], v[178:179] op_sel_hi:[1,0]
	v_pk_mul_f32 v[46:47], v[46:47], v[178:179] op_sel_hi:[1,0]
	v_pk_mul_f32 v[44:45], v[44:45], v[178:179] op_sel_hi:[1,0]
	v_pk_mul_f32 v[42:43], v[42:43], v[178:179] op_sel_hi:[1,0]
	v_pk_mul_f32 v[40:41], v[40:41], v[178:179] op_sel_hi:[1,0]
	v_pk_mul_f32 v[38:39], v[38:39], v[178:179] op_sel_hi:[1,0]
	v_pk_mul_f32 v[36:37], v[36:37], v[178:179] op_sel_hi:[1,0]
	v_pk_mul_f32 v[34:35], v[34:35], v[178:179] op_sel_hi:[1,0]

.LBB0_1067:
	s_nop 3
	s_nop 0
	v_max3_f32 v114, v83, v67, v84
	v_max3_f32 v114, v114, v68, v85
	v_max3_f32 v114, v114, v69, v66
	v_max3_f32 v114, v114, v82, v86
	v_max3_f32 v114, v114, v70, v87
	v_max3_f32 v114, v114, v71, v88
	v_max3_f32 v114, v114, v72, v89
	v_max3_f32 v114, v114, v73, v90
	v_max3_f32 v114, v114, v74, v91
	v_max3_f32 v114, v114, v75, v92
	v_max3_f32 v114, v114, v76, v93
	v_max3_f32 v114, v114, v77, v94
	v_max3_f32 v114, v114, v78, v95
	v_max3_f32 v114, v114, v79, v96
	v_max3_f32 v114, v114, v80, v97
	v_max_f32_e32 v114, v114, v81
	v_and_b32_e32 v116, 64, v218
	v_xor_b32_e32 v115, 32, v218
	v_add_u32_e32 v116, 64, v116
	v_cmp_lt_i32_e32 vcc, v115, v116
	s_nop 1
	v_cndmask_b32_e32 v115, v218, v115, vcc
	v_lshlrev_b32_e32 v115, 2, v115
	ds_bpermute_b32 v115, v115, v114
	s_waitcnt lgkmcnt(0)
	v_max3_f32 v206, v204, v114, v115
	v_sub_f32_e32 v114, v204, v206
	v_cmp_gt_f32_e32 vcc, 0xc1000000, v114
	s_cbranch_vccnz .Llazy5_full
	v_mov_b32_e32 v206, v204
	v_mov_b32_e32 v114, 1.0
	s_branch .LBB0_1069
.Llazy5_full:
	v_exp_f32_e32 v114, v114
	s_nop 0
	v_cmp_neq_f32_e32 vcc, 1.0, v114
	s_cbranch_vccz .LBB0_1069
	v_pk_mul_f32 v[16:17], v[16:17], v[114:115] op_sel_hi:[1,0]
	v_pk_mul_f32 v[14:15], v[14:15], v[114:115] op_sel_hi:[1,0]
	v_pk_mul_f32 v[12:13], v[12:13], v[114:115] op_sel_hi:[1,0]
	v_pk_mul_f32 v[10:11], v[10:11], v[114:115] op_sel_hi:[1,0]
	v_pk_mul_f32 v[8:9], v[8:9], v[114:115] op_sel_hi:[1,0]
	v_pk_mul_f32 v[6:7], v[6:7], v[114:115] op_sel_hi:[1,0]
	v_pk_mul_f32 v[4:5], v[4:5], v[114:115] op_sel_hi:[1,0]
	v_pk_mul_f32 v[2:3], v[2:3], v[114:115] op_sel_hi:[1,0]
	v_pk_mul_f32 v[32:33], v[32:33], v[114:115] op_sel_hi:[1,0]
	v_pk_mul_f32 v[30:31], v[30:31], v[114:115] op_sel_hi:[1,0]
	v_pk_mul_f32 v[28:29], v[28:29], v[114:115] op_sel_hi:[1,0]
	v_pk_mul_f32 v[26:27], v[26:27], v[114:115] op_sel_hi:[1,0]
	v_pk_mul_f32 v[24:25], v[24:25], v[114:115] op_sel_hi:[1,0]
	v_pk_mul_f32 v[22:23], v[22:23], v[114:115] op_sel_hi:[1,0]
	v_pk_mul_f32 v[20:21], v[20:21], v[114:115] op_sel_hi:[1,0]
	v_pk_mul_f32 v[18:19], v[18:19], v[114:115] op_sel_hi:[1,0]

.LBB0_1107:
	s_waitcnt lgkmcnt(0)
	s_nop 3
	s_nop 0
	v_max3_f32 v178, v99, v115, v100
	v_max3_f32 v178, v178, v116, v101
	v_max3_f32 v178, v178, v117, v114
	v_max3_f32 v178, v178, v98, v102
	v_max3_f32 v178, v178, v118, v103
	v_max3_f32 v178, v178, v119, v104
	v_max3_f32 v178, v178, v120, v105
	v_max3_f32 v178, v178, v121, v106
	v_max3_f32 v178, v178, v122, v107
	v_max3_f32 v178, v178, v123, v108
	v_max3_f32 v178, v178, v124, v109
	v_max3_f32 v178, v178, v125, v110
	v_max3_f32 v178, v178, v126, v111
	v_max3_f32 v178, v178, v127, v112
	v_max3_f32 v178, v178, v128, v113
	v_max_f32_e32 v178, v178, v129
	v_and_b32_e32 v180, 64, v218
	v_xor_b32_e32 v179, 32, v218
	v_add_u32_e32 v180, 64, v180
	v_cmp_lt_i32_e32 vcc, v179, v180
	s_nop 1
	v_cndmask_b32_e32 v179, v218, v179, vcc
	v_lshlrev_b32_e32 v179, 2, v179
	ds_bpermute_b32 v179, v179, v178
	s_waitcnt lgkmcnt(0)
	v_max3_f32 v205, v207, v178, v179
	v_sub_f32_e32 v178, v207, v205
	v_cmp_gt_f32_e32 vcc, 0xc1000000, v178
	s_cbranch_vccnz .Llazy6_full
	v_mov_b32_e32 v205, v207
	v_mov_b32_e32 v178, 1.0
	s_branch .LBB0_1109

.LBB0_1124:
	s_nop 3
	s_nop 0
	v_max3_f32 v114, v83, v67, v84
	v_max3_f32 v114, v114, v68, v85
	v_max3_f32 v114, v114, v69, v66
	v_max3_f32 v114, v114, v82, v86
	v_max3_f32 v114, v114, v70, v87
	v_max3_f32 v114, v114, v71, v88
	v_max3_f32 v114, v114, v72, v89
	v_max3_f32 v114, v114, v73, v90
	v_max3_f32 v114, v114, v74, v91
	v_max3_f32 v114, v114, v75, v92
	v_max3_f32 v114, v114, v76, v93
	v_max3_f32 v114, v114, v77, v94
	v_max3_f32 v114, v114, v78, v95
	v_max3_f32 v114, v114, v79, v96
	v_max3_f32 v114, v114, v80, v97
	v_max_f32_e32 v114, v114, v81
	v_and_b32_e32 v116, 64, v218
	v_xor_b32_e32 v115, 32, v218
	v_add_u32_e32 v116, 64, v116
	v_cmp_lt_i32_e32 vcc, v115, v116
	s_nop 1
	v_cndmask_b32_e32 v115, v218, v115, vcc
	v_lshlrev_b32_e32 v115, 2, v115
	ds_bpermute_b32 v115, v115, v114
	s_waitcnt lgkmcnt(0)
	v_max3_f32 v204, v206, v114, v115
	v_sub_f32_e32 v114, v206, v204
	v_cmp_gt_f32_e32 vcc, 0xc1000000, v114
	s_cbranch_vccnz .Llazy7_full
	v_mov_b32_e32 v204, v206
	v_mov_b32_e32 v114, 1.0
	s_branch .LBB0_1126

.LBB0_1165:
	s_sub_i32 s45, s42, 64
	s_cmp_ge_u32 s45, s66
	s_cselect_b64 s[48:49], -1, 0
	s_cmp_gt_i32 s44, s39
	s_cselect_b64 s[50:51], -1, 0
	s_or_b64 s[48:49], s[50:51], s[48:49]
	s_and_b64 vcc, exec, s[48:49]
	s_cbranch_vccnz .LBB0_1169
	v_add_u32_e32 v120, v124, v198
	ds_read_b128 v[136:139], v120
	ds_read_b128 v[140:143], v120 offset:6656
	ds_read_b128 v[144:147], v120 offset:32
	ds_read_b128 v[148:151], v120 offset:6688
	ds_read_b128 v[152:155], v120 offset:64
	ds_read_b128 v[156:159], v120 offset:6720
	ds_read_b128 v[160:163], v120 offset:96
	ds_read_b128 v[164:167], v120 offset:6752
	ds_read_b128 v[168:171], v120 offset:128
	ds_read_b128 v[172:175], v120 offset:6784
	ds_read_b128 v[176:179], v120 offset:160
	ds_read_b128 v[180:183], v120 offset:6816
	v_add_u32_e32 v184, v125, v126
	s_waitcnt lgkmcnt(11)
	v_mfma_f32_32x32x16_bf16 v[34:49], v[136:139], v[66:69], 0
	s_waitcnt lgkmcnt(10)
	v_mfma_f32_32x32x16_bf16 v[50:65], v[140:143], v[66:69], 0
	s_waitcnt lgkmcnt(9)
	v_mfma_f32_32x32x16_bf16 v[34:49], v[144:147], v[70:73], v[34:49]
	s_waitcnt lgkmcnt(8)
	v_mfma_f32_32x32x16_bf16 v[50:65], v[148:151], v[70:73], v[50:65]
	s_waitcnt lgkmcnt(7)
	v_mfma_f32_32x32x16_bf16 v[34:49], v[152:155], v[74:77], v[34:49]
	s_waitcnt lgkmcnt(6)
	v_mfma_f32_32x32x16_bf16 v[50:65], v[156:159], v[74:77], v[50:65]
	s_waitcnt lgkmcnt(5)
	v_mfma_f32_32x32x16_bf16 v[34:49], v[160:163], v[78:81], v[34:49]
	s_waitcnt lgkmcnt(4)
	v_mfma_f32_32x32x16_bf16 v[50:65], v[164:167], v[78:81], v[50:65]
	s_waitcnt lgkmcnt(3)
	v_mfma_f32_32x32x16_bf16 v[34:49], v[168:171], v[106:109], v[34:49]
	s_waitcnt lgkmcnt(2)
	v_mfma_f32_32x32x16_bf16 v[50:65], v[172:175], v[106:109], v[50:65]
	s_waitcnt lgkmcnt(1)
	v_mfma_f32_32x32x16_bf16 v[34:49], v[176:179], v[110:113], v[34:49]
	s_waitcnt lgkmcnt(0)
	v_mfma_f32_32x32x16_bf16 v[50:65], v[180:183], v[110:113], v[50:65]
	s_nop 11
	v_max3_f32 v120, v34, v35, v36
	v_max3_f32 v120, v120, v37, v38
	v_max3_f32 v120, v120, v39, v40
	v_max3_f32 v120, v120, v41, v42
	v_max3_f32 v120, v120, v43, v44
	v_max3_f32 v120, v120, v45, v46
	v_max3_f32 v120, v120, v47, v48
	v_max3_f32 v120, v120, v49, v50
	v_max3_f32 v120, v120, v51, v52
	v_max3_f32 v120, v120, v53, v54
	v_max3_f32 v120, v120, v55, v56
	v_max3_f32 v120, v120, v57, v58
	v_max3_f32 v120, v120, v59, v60
	v_max3_f32 v120, v120, v61, v62
	v_max3_f32 v120, v120, v63, v64
	v_max_f32_e32 v120, v120, v65
	v_and_b32_e32 v131, 64, v218
	v_xor_b32_e32 v130, 32, v218
	v_add_u32_e32 v131, 64, v131
	v_cmp_lt_i32_e32 vcc, v130, v131
	s_nop 1
	v_cndmask_b32_e32 v130, v218, v130, vcc
	v_lshlrev_b32_e32 v130, 2, v130
	ds_bpermute_b32 v130, v130, v120
	s_waitcnt lgkmcnt(0)
	ds_read_b64_tr_b16 v[136:137], v184 offset:13312
	ds_read_b64_tr_b16 v[138:139], v184 offset:14464
	ds_read_b64_tr_b16 v[140:141], v184 offset:13376
	ds_read_b64_tr_b16 v[142:143], v184 offset:14528
	ds_read_b64_tr_b16 v[144:145], v184 offset:15616
	ds_read_b64_tr_b16 v[146:147], v184 offset:16768
	ds_read_b64_tr_b16 v[148:149], v184 offset:15680
	ds_read_b64_tr_b16 v[150:151], v184 offset:16832
	ds_read_b64_tr_b16 v[152:153], v184 offset:17920
	ds_read_b64_tr_b16 v[154:155], v184 offset:19072
	ds_read_b64_tr_b16 v[156:157], v184 offset:17984
	ds_read_b64_tr_b16 v[158:159], v184 offset:19136
	ds_read_b64_tr_b16 v[160:161], v184 offset:20224
	ds_read_b64_tr_b16 v[162:163], v184 offset:21376
	ds_read_b64_tr_b16 v[164:165], v184 offset:20288
	ds_read_b64_tr_b16 v[166:167], v184 offset:21440
	v_max3_f32 v130, v129, v120, v130
	v_sub_f32_e32 v120, v129, v130
	v_cmp_gt_f32_e32 vcc, 0xc1000000, v120
	s_cbranch_vccnz .Llazy8_full
	v_mov_b32_e32 v130, v129
	v_mov_b32_e32 v120, 1.0
	s_branch .LBB0_1168
.Llazy8_full:
	v_exp_f32_e32 v120, v120
	s_nop 0
	v_cmp_neq_f32_e32 vcc, 1.0, v120
	s_cbranch_vccz .LBB0_1168
	v_pk_mul_f32 v[16:17], v[16:17], v[120:121] op_sel_hi:[1,0]
	v_pk_mul_f32 v[14:15], v[14:15], v[120:121] op_sel_hi:[1,0]
	v_pk_mul_f32 v[12:13], v[12:13], v[120:121] op_sel_hi:[1,0]
	v_pk_mul_f32 v[10:11], v[10:11], v[120:121] op_sel_hi:[1,0]
	v_pk_mul_f32 v[8:9], v[8:9], v[120:121] op_sel_hi:[1,0]
	v_pk_mul_f32 v[6:7], v[6:7], v[120:121] op_sel_hi:[1,0]
	v_pk_mul_f32 v[4:5], v[4:5], v[120:121] op_sel_hi:[1,0]
	v_pk_mul_f32 v[2:3], v[2:3], v[120:121] op_sel_hi:[1,0]
	v_pk_mul_f32 v[32:33], v[32:33], v[120:121] op_sel_hi:[1,0]
	v_pk_mul_f32 v[30:31], v[30:31], v[120:121] op_sel_hi:[1,0]
	v_pk_mul_f32 v[28:29], v[28:29], v[120:121] op_sel_hi:[1,0]
	v_pk_mul_f32 v[26:27], v[26:27], v[120:121] op_sel_hi:[1,0]
	v_pk_mul_f32 v[24:25], v[24:25], v[120:121] op_sel_hi:[1,0]
	v_pk_mul_f32 v[22:23], v[22:23], v[120:121] op_sel_hi:[1,0]
	v_pk_mul_f32 v[20:21], v[20:21], v[120:121] op_sel_hi:[1,0]
	v_pk_mul_f32 v[18:19], v[18:19], v[120:121] op_sel_hi:[1,0]

.LBB0_1179:
	s_cmp_ge_u32 s42, s66
	s_cselect_b64 s[48:49], -1, 0
	s_cmp_ge_i32 s44, s39
	s_cselect_b64 s[50:51], -1, 0
	s_or_b64 s[48:49], s[50:51], s[48:49]
	s_and_b64 vcc, exec, s[48:49]
	s_cbranch_vccnz .LBB0_1184
	v_add_u32_e32 v120, v124, v198
	ds_read_b128 v[136:139], v120 offset:32768
	ds_read_b128 v[140:143], v120 offset:39424
	ds_read_b128 v[144:147], v120 offset:32800
	ds_read_b128 v[148:151], v120 offset:39456
	ds_read_b128 v[152:155], v120 offset:32832
	ds_read_b128 v[156:159], v120 offset:39488
	ds_read_b128 v[160:163], v120 offset:32864
	ds_read_b128 v[164:167], v120 offset:39520
	ds_read_b128 v[168:171], v120 offset:32896
	ds_read_b128 v[172:175], v120 offset:39552
	ds_read_b128 v[176:179], v120 offset:32928
	ds_read_b128 v[180:183], v120 offset:39584
	v_add_u32_e32 v184, v125, v126
	s_waitcnt lgkmcnt(11)
	v_mfma_f32_32x32x16_bf16 v[34:49], v[136:139], v[66:69], 0
	s_waitcnt lgkmcnt(10)
	v_mfma_f32_32x32x16_bf16 v[50:65], v[140:143], v[66:69], 0
	s_waitcnt lgkmcnt(9)
	v_mfma_f32_32x32x16_bf16 v[34:49], v[144:147], v[70:73], v[34:49]
	s_waitcnt lgkmcnt(8)
	v_mfma_f32_32x32x16_bf16 v[50:65], v[148:151], v[70:73], v[50:65]
	s_waitcnt lgkmcnt(7)
	v_mfma_f32_32x32x16_bf16 v[34:49], v[152:155], v[74:77], v[34:49]
	s_waitcnt lgkmcnt(6)
	v_mfma_f32_32x32x16_bf16 v[50:65], v[156:159], v[74:77], v[50:65]
	s_waitcnt lgkmcnt(5)
	v_mfma_f32_32x32x16_bf16 v[34:49], v[160:163], v[78:81], v[34:49]
	s_waitcnt lgkmcnt(4)
	v_mfma_f32_32x32x16_bf16 v[50:65], v[164:167], v[78:81], v[50:65]
	s_waitcnt lgkmcnt(3)
	v_mfma_f32_32x32x16_bf16 v[34:49], v[168:171], v[106:109], v[34:49]
	s_waitcnt lgkmcnt(2)
	v_mfma_f32_32x32x16_bf16 v[50:65], v[172:175], v[106:109], v[50:65]
	s_waitcnt lgkmcnt(1)
	v_mfma_f32_32x32x16_bf16 v[34:49], v[176:179], v[110:113], v[34:49]
	s_waitcnt lgkmcnt(0)
	v_mfma_f32_32x32x16_bf16 v[50:65], v[180:183], v[110:113], v[50:65]
	s_nop 11
	v_max3_f32 v120, v34, v35, v36
	v_max3_f32 v120, v120, v37, v38
	v_max3_f32 v120, v120, v39, v40
	v_max3_f32 v120, v120, v41, v42
	v_max3_f32 v120, v120, v43, v44
	v_max3_f32 v120, v120, v45, v46
	v_max3_f32 v120, v120, v47, v48
	v_max3_f32 v120, v120, v49, v50
	v_max3_f32 v120, v120, v51, v52
	v_max3_f32 v120, v120, v53, v54
	v_max3_f32 v120, v120, v55, v56
	v_max3_f32 v120, v120, v57, v58
	v_max3_f32 v120, v120, v59, v60
	v_max3_f32 v120, v120, v61, v62
	v_max3_f32 v120, v120, v63, v64
	v_max_f32_e32 v120, v120, v65
	v_and_b32_e32 v131, 64, v218
	v_xor_b32_e32 v129, 32, v218
	v_add_u32_e32 v131, 64, v131
	v_cmp_lt_i32_e32 vcc, v129, v131
	s_nop 1
	v_cndmask_b32_e32 v129, v218, v129, vcc
	v_lshlrev_b32_e32 v129, 2, v129
	ds_bpermute_b32 v129, v129, v120
	s_waitcnt lgkmcnt(0)
	ds_read_b64_tr_b16 v[136:137], v184 offset:46080
	ds_read_b64_tr_b16 v[138:139], v184 offset:47232
	ds_read_b64_tr_b16 v[140:141], v184 offset:46144
	ds_read_b64_tr_b16 v[142:143], v184 offset:47296
	ds_read_b64_tr_b16 v[144:145], v184 offset:48384
	ds_read_b64_tr_b16 v[146:147], v184 offset:49536
	ds_read_b64_tr_b16 v[148:149], v184 offset:48448
	ds_read_b64_tr_b16 v[150:151], v184 offset:49600
	ds_read_b64_tr_b16 v[152:153], v184 offset:50688
	ds_read_b64_tr_b16 v[154:155], v184 offset:51840
	ds_read_b64_tr_b16 v[156:157], v184 offset:50752
	ds_read_b64_tr_b16 v[158:159], v184 offset:51904
	ds_read_b64_tr_b16 v[160:161], v184 offset:52992
	ds_read_b64_tr_b16 v[162:163], v184 offset:54144
	ds_read_b64_tr_b16 v[164:165], v184 offset:53056
	ds_read_b64_tr_b16 v[166:167], v184 offset:54208
	v_max3_f32 v129, v130, v120, v129
	v_sub_f32_e32 v120, v130, v129
	v_cmp_gt_f32_e32 vcc, 0xc1000000, v120
	s_cbranch_vccnz .Llazy9_full
	v_mov_b32_e32 v129, v130
	v_mov_b32_e32 v120, 1.0
	s_branch .LBB0_1182
